# barrier spin loops: poll back-off s_sleep 1 -> 4 (fewer polls on the shared arrival-counter line while leaders' atomics are in flight)
# baseline (speedup 1.0000x reference)
; DI unsigned xb_ld(unsigned* p) { return __hip_atomic_load(p, __ATOMIC_RELAXED, __HIP_MEMORY_SCOPE_AGENT); }
; DI void xcd_barrier_complete(unsigned* bar, unsigned x, unsigned& nloc, unsigned& nx) {
;     ...
;   for (;;) {
;     sum = 0u; cnt = 0u; mine = 0u;
; #pragma unroll
;     for (unsigned j = 0; j < 16; ++j) { const unsigned c = xb_ld(&bar[XB_XCNT(j)]); sum += c; cnt += (c > 0u) ? 1u : 0u; mine = (j == x) ? c : mine; }
;     if (sum == G) break;
;     __builtin_amdgcn_s_sleep(1);
;     if ((++sp & 255u) == 0u) { if (xb_ld(&bar[XB_TMO])) break; if (sp > XB_SPIN_CAP) { atomicAdd(&bar[XB_TMO], 1u); break; } }
;   }
.LBB0_71:
	global_load_dword v16, v17, s[12:13] sc1
	global_load_dword v1, v17, s[14:15] sc1
	global_load_dword v2, v17, s[16:17] sc1
	global_load_dword v3, v17, s[18:19] sc1
	global_load_dword v4, v17, s[22:23] sc1
	global_load_dword v5, v17, s[24:25] sc1
	global_load_dword v6, v17, s[26:27] sc1
	global_load_dword v7, v17, s[28:29] sc1
	global_load_dword v8, v17, s[30:31] sc1
	global_load_dword v9, v17, s[34:35] sc1
	global_load_dword v10, v17, s[36:37] sc1
	global_load_dword v11, v17, s[38:39] sc1
	global_load_dword v12, v17, s[40:41] sc1
	global_load_dword v13, v17, s[42:43] sc1
	global_load_dword v14, v17, s[44:45] sc1
	global_load_dword v15, v17, s[46:47] sc1
	s_mov_b64 s[48:49], -1
	s_mov_b64 s[50:51], -1
	s_waitcnt vmcnt(14)
	v_add_u32_e32 v18, v1, v16
	s_waitcnt vmcnt(13)
	v_add_u32_e32 v18, v18, v2
	s_waitcnt vmcnt(12)
	v_add_u32_e32 v18, v18, v3
	s_waitcnt vmcnt(11)
	v_add_u32_e32 v18, v18, v4
	s_waitcnt vmcnt(10)
	v_add_u32_e32 v18, v18, v5
	s_waitcnt vmcnt(9)
	v_add_u32_e32 v18, v18, v6
	s_waitcnt vmcnt(8)
	v_add_u32_e32 v18, v18, v7
	s_waitcnt vmcnt(7)
	v_add_u32_e32 v18, v18, v8
	s_waitcnt vmcnt(6)
	v_add_u32_e32 v18, v18, v9
	s_waitcnt vmcnt(5)
	v_add_u32_e32 v18, v18, v10
	s_waitcnt vmcnt(4)
	v_add_u32_e32 v18, v18, v11
	s_waitcnt vmcnt(3)
	v_add_u32_e32 v18, v18, v12
	s_waitcnt vmcnt(2)
	v_add_u32_e32 v18, v18, v13
	s_waitcnt vmcnt(1)
	v_add_u32_e32 v18, v18, v14
	s_waitcnt vmcnt(0)
	v_add_u32_e32 v18, v18, v15
	v_cmp_eq_u32_e32 vcc, s3, v18
	s_cbranch_vccnz .LBB0_70
	s_and_b32 s5, s4, 0xff
	s_cmp_eq_u32 s5, 0
	s_mov_b64 s[52:53], -1
	s_sleep 4
	s_cbranch_scc1 .LBB0_75
	s_and_b64 vcc, exec, s[52:53]
	s_cbranch_vccz .LBB0_70

.LBB0_89:
	s_and_b32 s3, s2, 0xff
	s_mov_b64 s[26:27], -1
	s_cmp_lg_u32 s3, 0
	s_mov_b64 s[30:31], -1
	s_sleep 4
	s_cbranch_scc0 .LBB0_92
	s_and_b64 vcc, exec, s[30:31]
	s_cbranch_vccz .LBB0_88

.LBB0_106:
	s_and_b32 s3, s2, 0xff
	s_cmp_lg_u32 s3, 0
	s_mov_b64 s[26:27], -1
	s_sleep 4
	s_cbranch_scc0 .LBB0_109
	s_mov_b64 s[28:29], -1
	s_and_b64 vcc, exec, s[26:27]
	s_cbranch_vccz .LBB0_105

; DI unsigned xb_ld(unsigned* p) { return __hip_atomic_load(p, __ATOMIC_RELAXED, __HIP_MEMORY_SCOPE_AGENT); }
; DI void xcd_barrier_complete(unsigned* bar, unsigned x, unsigned& nloc, unsigned& nx) {
;     ...
;   for (;;) {
;     sum = 0u; cnt = 0u; mine = 0u;
; #pragma unroll
;     for (unsigned j = 0; j < 16; ++j) { const unsigned c = xb_ld(&bar[XB_XCNT(j)]); sum += c; cnt += (c > 0u) ? 1u : 0u; mine = (j == x) ? c : mine; }
;     if (sum == G) break;
;     __builtin_amdgcn_s_sleep(1);
;     if ((++sp & 255u) == 0u) { if (xb_ld(&bar[XB_TMO])) break; if (sp > XB_SPIN_CAP) { atomicAdd(&bar[XB_TMO], 1u); break; } }
;   }
.LBB0_265:
	global_load_dword v17, v199, s[12:13] sc1
	global_load_dword v2, v199, s[14:15] sc1
	global_load_dword v3, v199, s[18:19] sc1
	global_load_dword v4, v199, s[22:23] sc1
	global_load_dword v5, v199, s[24:25] sc1
	global_load_dword v6, v199, s[26:27] sc1
	global_load_dword v7, v199, s[28:29] sc1
	global_load_dword v8, v199, s[34:35] sc1
	global_load_dword v9, v199, s[36:37] sc1
	global_load_dword v10, v199, s[84:85] sc1
	global_load_dword v11, v199, s[86:87] sc1
	global_load_dword v12, v199, s[88:89] sc1
	global_load_dword v13, v199, s[90:91] sc1
	global_load_dword v14, v199, s[92:93] sc1
	global_load_dword v15, v199, s[94:95] sc1
	global_load_dword v16, v199, s[96:97] sc1
	s_mov_b64 s[52:53], -1
	s_mov_b64 s[54:55], -1
	s_waitcnt vmcnt(14)
	v_add_u32_e32 v18, v2, v17
	s_waitcnt vmcnt(13)
	v_add_u32_e32 v18, v18, v3
	s_waitcnt vmcnt(12)
	v_add_u32_e32 v18, v18, v4
	s_waitcnt vmcnt(11)
	v_add_u32_e32 v18, v18, v5
	s_waitcnt vmcnt(10)
	v_add_u32_e32 v18, v18, v6
	s_waitcnt vmcnt(9)
	v_add_u32_e32 v18, v18, v7
	s_waitcnt vmcnt(8)
	v_add_u32_e32 v18, v18, v8
	s_waitcnt vmcnt(7)
	v_add_u32_e32 v18, v18, v9
	s_waitcnt vmcnt(6)
	v_add_u32_e32 v18, v18, v10
	s_waitcnt vmcnt(5)
	v_add_u32_e32 v18, v18, v11
	s_waitcnt vmcnt(4)
	v_add_u32_e32 v18, v18, v12
	s_waitcnt vmcnt(3)
	v_add_u32_e32 v18, v18, v13
	s_waitcnt vmcnt(2)
	v_add_u32_e32 v18, v18, v14
	s_waitcnt vmcnt(1)
	v_add_u32_e32 v18, v18, v15
	s_waitcnt vmcnt(0)
	v_add_u32_e32 v18, v18, v16
	v_cmp_eq_u32_e32 vcc, s3, v18
	s_cbranch_vccnz .LBB0_264
	s_and_b32 s5, s4, 0xff
	s_cmp_eq_u32 s5, 0
	s_mov_b64 vcc, -1
	s_sleep 4
	s_cbranch_scc1 .LBB0_269
	s_and_b64 vcc, exec, vcc
	s_cbranch_vccz .LBB0_264

.LBB0_283:
	s_and_b32 s3, s2, 0xff
	s_mov_b64 s[28:29], -1
	s_cmp_lg_u32 s3, 0
	s_mov_b64 s[36:37], -1
	s_sleep 4
	s_cbranch_scc0 .LBB0_286
	s_and_b64 vcc, exec, s[36:37]
	s_cbranch_vccz .LBB0_282

.LBB0_300:
	s_and_b32 s3, s2, 0xff
	s_mov_b64 s[26:27], -1
	s_cmp_lg_u32 s3, 0
	s_mov_b64 s[34:35], -1
	s_sleep 4
	s_cbranch_scc0 .LBB0_303
	s_and_b64 vcc, exec, s[34:35]
	s_cbranch_vccz .LBB0_299

; DI unsigned xb_ld(unsigned* p) { return __hip_atomic_load(p, __ATOMIC_RELAXED, __HIP_MEMORY_SCOPE_AGENT); }
; DI void xcd_barrier_complete(unsigned* bar, unsigned x, unsigned& nloc, unsigned& nx) {
;     ...
;   for (;;) {
;     sum = 0u; cnt = 0u; mine = 0u;
; #pragma unroll
;     for (unsigned j = 0; j < 16; ++j) { const unsigned c = xb_ld(&bar[XB_XCNT(j)]); sum += c; cnt += (c > 0u) ? 1u : 0u; mine = (j == x) ? c : mine; }
;     if (sum == G) break;
;     __builtin_amdgcn_s_sleep(1);
;     if ((++sp & 255u) == 0u) { if (xb_ld(&bar[XB_TMO])) break; if (sp > XB_SPIN_CAP) { atomicAdd(&bar[XB_TMO], 1u); break; } }
;   }
.LBB0_507:
	global_load_dword v17, v199, s[12:13] sc1
	global_load_dword v2, v199, s[14:15] sc1
	global_load_dword v3, v199, s[16:17] sc1
	global_load_dword v4, v199, s[18:19] sc1
	global_load_dword v5, v199, s[22:23] sc1
	global_load_dword v6, v199, s[24:25] sc1
	global_load_dword v7, v199, s[26:27] sc1
	global_load_dword v8, v199, s[28:29] sc1
	global_load_dword v9, v199, s[34:35] sc1
	global_load_dword v10, v199, s[36:37] sc1
	global_load_dword v11, v199, s[84:85] sc1
	global_load_dword v12, v199, s[86:87] sc1
	global_load_dword v13, v199, s[88:89] sc1
	global_load_dword v14, v199, s[90:91] sc1
	global_load_dword v15, v199, s[92:93] sc1
	global_load_dword v16, v199, s[94:95] sc1
	s_mov_b64 s[52:53], -1
	s_mov_b64 s[54:55], -1
	s_waitcnt vmcnt(14)
	v_add_u32_e32 v18, v2, v17
	s_waitcnt vmcnt(13)
	v_add_u32_e32 v18, v18, v3
	s_waitcnt vmcnt(12)
	v_add_u32_e32 v18, v18, v4
	s_waitcnt vmcnt(11)
	v_add_u32_e32 v18, v18, v5
	s_waitcnt vmcnt(10)
	v_add_u32_e32 v18, v18, v6
	s_waitcnt vmcnt(9)
	v_add_u32_e32 v18, v18, v7
	s_waitcnt vmcnt(8)
	v_add_u32_e32 v18, v18, v8
	s_waitcnt vmcnt(7)
	v_add_u32_e32 v18, v18, v9
	s_waitcnt vmcnt(6)
	v_add_u32_e32 v18, v18, v10
	s_waitcnt vmcnt(5)
	v_add_u32_e32 v18, v18, v11
	s_waitcnt vmcnt(4)
	v_add_u32_e32 v18, v18, v12
	s_waitcnt vmcnt(3)
	v_add_u32_e32 v18, v18, v13
	s_waitcnt vmcnt(2)
	v_add_u32_e32 v18, v18, v14
	s_waitcnt vmcnt(1)
	v_add_u32_e32 v18, v18, v15
	s_waitcnt vmcnt(0)
	v_add_u32_e32 v18, v18, v16
	v_cmp_eq_u32_e32 vcc, s3, v18
	s_cbranch_vccnz .LBB0_506
	s_and_b32 s5, s4, 0xff
	s_cmp_eq_u32 s5, 0
	s_mov_b64 s[96:97], -1
	s_sleep 4
	s_cbranch_scc1 .LBB0_511
	s_and_b64 vcc, exec, s[96:97]
	s_cbranch_vccz .LBB0_506

.LBB0_896:
	s_and_b32 s3, s2, 0xff
	s_mov_b64 s[24:25], -1
	s_cmp_lg_u32 s3, 0
	s_mov_b64 s[28:29], -1
	s_sleep 4
	s_cbranch_scc0 .LBB0_899
	s_and_b64 vcc, exec, s[28:29]
	s_cbranch_vccz .LBB0_895

; DI unsigned xb_ld(unsigned* p) { return __hip_atomic_load(p, __ATOMIC_RELAXED, __HIP_MEMORY_SCOPE_AGENT); }
; DI void xcd_barrier_complete(unsigned* bar, unsigned x, unsigned& nloc, unsigned& nx) {
;   const unsigned G = gridDim.x * gridDim.y * gridDim.z;
;   unsigned sum, cnt, mine, sp = 0u;
;   for (;;) {
;     sum = 0u; cnt = 0u; mine = 0u;
; #pragma unroll
;     for (unsigned j = 0; j < 16; ++j) { const unsigned c = xb_ld(&bar[XB_XCNT(j)]); sum += c; cnt += (c > 0u) ? 1u : 0u; mine = (j == x) ? c : mine; }
;     if (sum == G) break;
;     __builtin_amdgcn_s_sleep(1);
;     if ((++sp & 255u) == 0u) { if (xb_ld(&bar[XB_TMO])) break; if (sp > XB_SPIN_CAP) { atomicAdd(&bar[XB_TMO], 1u); break; } }
;   }
.LBB0_1104:
	global_load_dword v17, v199, s[12:13] sc1
	global_load_dword v2, v199, s[14:15] sc1
	global_load_dword v3, v199, s[16:17] sc1
	global_load_dword v4, v199, s[18:19] sc1
	global_load_dword v5, v199, s[22:23] sc1
	global_load_dword v6, v199, s[24:25] sc1
	global_load_dword v7, v199, s[26:27] sc1
	global_load_dword v8, v199, s[28:29] sc1
	global_load_dword v9, v199, s[34:35] sc1
	global_load_dword v10, v199, s[36:37] sc1
	global_load_dword v11, v199, s[82:83] sc1
	global_load_dword v12, v199, s[84:85] sc1
	global_load_dword v13, v199, s[86:87] sc1
	global_load_dword v14, v199, s[88:89] sc1
	global_load_dword v15, v199, s[90:91] sc1
	global_load_dword v16, v199, s[92:93] sc1
	s_mov_b64 s[52:53], -1
	s_mov_b64 s[54:55], -1
	s_waitcnt vmcnt(14)
	v_add_u32_e32 v18, v2, v17
	s_waitcnt vmcnt(13)
	v_add_u32_e32 v18, v18, v3
	s_waitcnt vmcnt(12)
	v_add_u32_e32 v18, v18, v4
	s_waitcnt vmcnt(11)
	v_add_u32_e32 v18, v18, v5
	s_waitcnt vmcnt(10)
	v_add_u32_e32 v18, v18, v6
	s_waitcnt vmcnt(9)
	v_add_u32_e32 v18, v18, v7
	s_waitcnt vmcnt(8)
	v_add_u32_e32 v18, v18, v8
	s_waitcnt vmcnt(7)
	v_add_u32_e32 v18, v18, v9
	s_waitcnt vmcnt(6)
	v_add_u32_e32 v18, v18, v10
	s_waitcnt vmcnt(5)
	v_add_u32_e32 v18, v18, v11
	s_waitcnt vmcnt(4)
	v_add_u32_e32 v18, v18, v12
	s_waitcnt vmcnt(3)
	v_add_u32_e32 v18, v18, v13
	s_waitcnt vmcnt(2)
	v_add_u32_e32 v18, v18, v14
	s_waitcnt vmcnt(1)
	v_add_u32_e32 v18, v18, v15
	s_waitcnt vmcnt(0)
	v_add_u32_e32 v18, v18, v16
	v_cmp_eq_u32_e32 vcc, s3, v18
	s_cbranch_vccnz .LBB0_1103
	s_and_b32 s5, s4, 0xff
	s_cmp_eq_u32 s5, 0
	s_mov_b64 s[94:95], -1
	s_sleep 4
	s_cbranch_scc1 .LBB0_1108
	s_and_b64 vcc, exec, s[94:95]
	s_cbranch_vccz .LBB0_1103

; DI unsigned xb_ld(unsigned* p) { return __hip_atomic_load(p, __ATOMIC_RELAXED, __HIP_MEMORY_SCOPE_AGENT); }
; DI void xcd_barrier_complete(unsigned* bar, unsigned x, unsigned& nloc, unsigned& nx) {
;   const unsigned G = gridDim.x * gridDim.y * gridDim.z;
;   unsigned sum, cnt, mine, sp = 0u;
;   for (;;) {
;     sum = 0u; cnt = 0u; mine = 0u;
; #pragma unroll
;     for (unsigned j = 0; j < 16; ++j) { const unsigned c = xb_ld(&bar[XB_XCNT(j)]); sum += c; cnt += (c > 0u) ? 1u : 0u; mine = (j == x) ? c : mine; }
;     if (sum == G) break;
;     __builtin_amdgcn_s_sleep(1);
;     if ((++sp & 255u) == 0u) { if (xb_ld(&bar[XB_TMO])) break; if (sp > XB_SPIN_CAP) { atomicAdd(&bar[XB_TMO], 1u); break; } }
;   }
.LBB0_1658:
	global_load_dword v17, v199, s[12:13] sc1
	global_load_dword v2, v199, s[14:15] sc1
	global_load_dword v3, v199, s[16:17] sc1
	global_load_dword v4, v199, s[18:19] sc1
	global_load_dword v5, v199, s[22:23] sc1
	global_load_dword v6, v199, s[24:25] sc1
	global_load_dword v7, v199, s[26:27] sc1
	global_load_dword v8, v199, s[28:29] sc1
	global_load_dword v9, v199, s[34:35] sc1
	global_load_dword v10, v199, s[36:37] sc1
	global_load_dword v11, v199, s[80:81] sc1
	global_load_dword v12, v199, s[82:83] sc1
	global_load_dword v13, v199, s[84:85] sc1
	global_load_dword v14, v199, s[86:87] sc1
	global_load_dword v15, v199, s[88:89] sc1
	global_load_dword v16, v199, s[90:91] sc1
	s_mov_b64 s[52:53], -1
	s_mov_b64 s[54:55], -1
	s_waitcnt vmcnt(14)
	v_add_u32_e32 v18, v2, v17
	s_waitcnt vmcnt(13)
	v_add_u32_e32 v18, v18, v3
	s_waitcnt vmcnt(12)
	v_add_u32_e32 v18, v18, v4
	s_waitcnt vmcnt(11)
	v_add_u32_e32 v18, v18, v5
	s_waitcnt vmcnt(10)
	v_add_u32_e32 v18, v18, v6
	s_waitcnt vmcnt(9)
	v_add_u32_e32 v18, v18, v7
	s_waitcnt vmcnt(8)
	v_add_u32_e32 v18, v18, v8
	s_waitcnt vmcnt(7)
	v_add_u32_e32 v18, v18, v9
	s_waitcnt vmcnt(6)
	v_add_u32_e32 v18, v18, v10
	s_waitcnt vmcnt(5)
	v_add_u32_e32 v18, v18, v11
	s_waitcnt vmcnt(4)
	v_add_u32_e32 v18, v18, v12
	s_waitcnt vmcnt(3)
	v_add_u32_e32 v18, v18, v13
	s_waitcnt vmcnt(2)
	v_add_u32_e32 v18, v18, v14
	s_waitcnt vmcnt(1)
	v_add_u32_e32 v18, v18, v15
	s_waitcnt vmcnt(0)
	v_add_u32_e32 v18, v18, v16
	v_cmp_eq_u32_e32 vcc, s3, v18
	s_cbranch_vccnz .LBB0_1657
	s_and_b32 s5, s4, 0xff
	s_cmp_eq_u32 s5, 0
	s_mov_b64 s[92:93], -1
	s_sleep 4
	s_cbranch_scc1 .LBB0_1662
	s_and_b64 vcc, exec, s[92:93]
	s_cbranch_vccz .LBB0_1657

; DI unsigned xb_ld(unsigned* p) { return __hip_atomic_load(p, __ATOMIC_RELAXED, __HIP_MEMORY_SCOPE_AGENT); }
; DI void xcd_barrier_complete(unsigned* bar, unsigned x, unsigned& nloc, unsigned& nx) {
;   const unsigned G = gridDim.x * gridDim.y * gridDim.z;
;   unsigned sum, cnt, mine, sp = 0u;
;   for (;;) {
;     sum = 0u; cnt = 0u; mine = 0u;
; #pragma unroll
;     for (unsigned j = 0; j < 16; ++j) { const unsigned c = xb_ld(&bar[XB_XCNT(j)]); sum += c; cnt += (c > 0u) ? 1u : 0u; mine = (j == x) ? c : mine; }
;     if (sum == G) break;
;     __builtin_amdgcn_s_sleep(1);
;     if ((++sp & 255u) == 0u) { if (xb_ld(&bar[XB_TMO])) break; if (sp > XB_SPIN_CAP) { atomicAdd(&bar[XB_TMO], 1u); break; } }
;   }
.LBB0_1805:
	global_load_dword v17, v199, s[16:17] sc1
	global_load_dword v2, v199, s[18:19] sc1
	global_load_dword v3, v199, s[22:23] sc1
	global_load_dword v4, v199, s[24:25] sc1
	global_load_dword v5, v199, s[26:27] sc1
	global_load_dword v6, v199, s[28:29] sc1
	global_load_dword v7, v199, s[34:35] sc1
	global_load_dword v8, v199, s[36:37] sc1
	global_load_dword v9, v199, s[80:81] sc1
	global_load_dword v10, v199, s[82:83] sc1
	global_load_dword v11, v199, s[84:85] sc1
	global_load_dword v12, v199, s[86:87] sc1
	global_load_dword v13, v199, s[88:89] sc1
	global_load_dword v14, v199, s[90:91] sc1
	global_load_dword v15, v199, s[92:93] sc1
	global_load_dword v16, v199, s[94:95] sc1
	s_mov_b64 s[52:53], -1
	s_mov_b64 s[54:55], -1
	s_waitcnt vmcnt(14)
	v_add_u32_e32 v18, v2, v17
	s_waitcnt vmcnt(13)
	v_add_u32_e32 v18, v18, v3
	s_waitcnt vmcnt(12)
	v_add_u32_e32 v18, v18, v4
	s_waitcnt vmcnt(11)
	v_add_u32_e32 v18, v18, v5
	s_waitcnt vmcnt(10)
	v_add_u32_e32 v18, v18, v6
	s_waitcnt vmcnt(9)
	v_add_u32_e32 v18, v18, v7
	s_waitcnt vmcnt(8)
	v_add_u32_e32 v18, v18, v8
	s_waitcnt vmcnt(7)
	v_add_u32_e32 v18, v18, v9
	s_waitcnt vmcnt(6)
	v_add_u32_e32 v18, v18, v10
	s_waitcnt vmcnt(5)
	v_add_u32_e32 v18, v18, v11
	s_waitcnt vmcnt(4)
	v_add_u32_e32 v18, v18, v12
	s_waitcnt vmcnt(3)
	v_add_u32_e32 v18, v18, v13
	s_waitcnt vmcnt(2)
	v_add_u32_e32 v18, v18, v14
	s_waitcnt vmcnt(1)
	v_add_u32_e32 v18, v18, v15
	s_waitcnt vmcnt(0)
	v_add_u32_e32 v18, v18, v16
	v_cmp_eq_u32_e32 vcc, s3, v18
	s_cbranch_vccnz .LBB0_1804
	s_and_b32 s5, s4, 0xff
	s_cmp_eq_u32 s5, 0
	s_mov_b64 s[96:97], -1
	s_sleep 4
	s_cbranch_scc1 .LBB0_1809
	s_and_b64 vcc, exec, s[96:97]
	s_cbranch_vccz .LBB0_1804

.LBB0_1823:
	s_and_b32 s3, s2, 0xff
	s_mov_b64 s[34:35], -1
	s_cmp_lg_u32 s3, 0
	s_mov_b64 s[52:53], -1
	s_sleep 4
	s_cbranch_scc0 .LBB0_1826
	s_and_b64 vcc, exec, s[52:53]
	s_cbranch_vccz .LBB0_1822

; DI unsigned xb_ld(unsigned* p) { return __hip_atomic_load(p, __ATOMIC_RELAXED, __HIP_MEMORY_SCOPE_AGENT); }
; DI void xcd_barrier_complete(unsigned* bar, unsigned x, unsigned& nloc, unsigned& nx) {
;   const unsigned G = gridDim.x * gridDim.y * gridDim.z;
;   unsigned sum, cnt, mine, sp = 0u;
;   for (;;) {
;     sum = 0u; cnt = 0u; mine = 0u;
; #pragma unroll
;     for (unsigned j = 0; j < 16; ++j) { const unsigned c = xb_ld(&bar[XB_XCNT(j)]); sum += c; cnt += (c > 0u) ? 1u : 0u; mine = (j == x) ? c : mine; }
;     if (sum == G) break;
;     __builtin_amdgcn_s_sleep(1);
;     if ((++sp & 255u) == 0u) { if (xb_ld(&bar[XB_TMO])) break; if (sp > XB_SPIN_CAP) { atomicAdd(&bar[XB_TMO], 1u); break; } }
;   }
.LBB0_1872:
	global_load_dword v17, v199, s[16:17] sc1
	global_load_dword v2, v199, s[18:19] sc1
	global_load_dword v3, v199, s[22:23] sc1
	global_load_dword v4, v199, s[24:25] sc1
	global_load_dword v5, v199, s[26:27] sc1
	global_load_dword v6, v199, s[28:29] sc1
	global_load_dword v7, v199, s[34:35] sc1
	global_load_dword v8, v199, s[36:37] sc1
	global_load_dword v9, v199, s[74:75] sc1
	global_load_dword v10, v199, s[76:77] sc1
	global_load_dword v11, v199, s[78:79] sc1
	global_load_dword v12, v199, s[80:81] sc1
	global_load_dword v13, v199, s[82:83] sc1
	global_load_dword v14, v199, s[84:85] sc1
	global_load_dword v15, v199, s[86:87] sc1
	global_load_dword v16, v199, s[88:89] sc1
	s_mov_b64 s[52:53], -1
	s_mov_b64 s[54:55], -1
	s_waitcnt vmcnt(14)
	v_add_u32_e32 v18, v2, v17
	s_waitcnt vmcnt(13)
	v_add_u32_e32 v18, v18, v3
	s_waitcnt vmcnt(12)
	v_add_u32_e32 v18, v18, v4
	s_waitcnt vmcnt(11)
	v_add_u32_e32 v18, v18, v5
	s_waitcnt vmcnt(10)
	v_add_u32_e32 v18, v18, v6
	s_waitcnt vmcnt(9)
	v_add_u32_e32 v18, v18, v7
	s_waitcnt vmcnt(8)
	v_add_u32_e32 v18, v18, v8
	s_waitcnt vmcnt(7)
	v_add_u32_e32 v18, v18, v9
	s_waitcnt vmcnt(6)
	v_add_u32_e32 v18, v18, v10
	s_waitcnt vmcnt(5)
	v_add_u32_e32 v18, v18, v11
	s_waitcnt vmcnt(4)
	v_add_u32_e32 v18, v18, v12
	s_waitcnt vmcnt(3)
	v_add_u32_e32 v18, v18, v13
	s_waitcnt vmcnt(2)
	v_add_u32_e32 v18, v18, v14
	s_waitcnt vmcnt(1)
	v_add_u32_e32 v18, v18, v15
	s_waitcnt vmcnt(0)
	v_add_u32_e32 v18, v18, v16
	v_cmp_eq_u32_e32 vcc, s3, v18
	s_cbranch_vccnz .LBB0_1871
	s_and_b32 s5, s4, 0xff
	s_cmp_eq_u32 s5, 0
	s_mov_b64 s[90:91], -1
	s_sleep 4
	s_cbranch_scc1 .LBB0_1876
	s_and_b64 vcc, exec, s[90:91]
	s_cbranch_vccz .LBB0_1871

; DI unsigned xb_ld(unsigned* p) { return __hip_atomic_load(p, __ATOMIC_RELAXED, __HIP_MEMORY_SCOPE_AGENT); }
; DI void xcd_barrier_complete(unsigned* bar, unsigned x, unsigned& nloc, unsigned& nx) {
;   const unsigned G = gridDim.x * gridDim.y * gridDim.z;
;   unsigned sum, cnt, mine, sp = 0u;
;   for (;;) {
;     sum = 0u; cnt = 0u; mine = 0u;
; #pragma unroll
;     for (unsigned j = 0; j < 16; ++j) { const unsigned c = xb_ld(&bar[XB_XCNT(j)]); sum += c; cnt += (c > 0u) ? 1u : 0u; mine = (j == x) ? c : mine; }
;     if (sum == G) break;
;     __builtin_amdgcn_s_sleep(1);
;     if ((++sp & 255u) == 0u) { if (xb_ld(&bar[XB_TMO])) break; if (sp > XB_SPIN_CAP) { atomicAdd(&bar[XB_TMO], 1u); break; } }
;   }
.LBB0_2025:
	global_load_dword v17, v199, s[12:13] sc1
	global_load_dword v2, v199, s[14:15] sc1
	global_load_dword v3, v199, s[16:17] sc1
	global_load_dword v4, v199, s[18:19] sc1
	global_load_dword v5, v199, s[22:23] sc1
	global_load_dword v6, v199, s[24:25] sc1
	global_load_dword v7, v199, s[26:27] sc1
	global_load_dword v8, v199, s[28:29] sc1
	global_load_dword v9, v199, s[34:35] sc1
	global_load_dword v10, v199, s[36:37] sc1
	global_load_dword v11, v199, s[74:75] sc1
	global_load_dword v12, v199, s[76:77] sc1
	global_load_dword v13, v199, s[78:79] sc1
	global_load_dword v14, v199, s[80:81] sc1
	global_load_dword v15, v199, s[82:83] sc1
	global_load_dword v16, v199, s[84:85] sc1
	s_mov_b64 s[52:53], -1
	s_mov_b64 s[54:55], -1
	s_waitcnt vmcnt(14)
	v_add_u32_e32 v18, v2, v17
	s_waitcnt vmcnt(13)
	v_add_u32_e32 v18, v18, v3
	s_waitcnt vmcnt(12)
	v_add_u32_e32 v18, v18, v4
	s_waitcnt vmcnt(11)
	v_add_u32_e32 v18, v18, v5
	s_waitcnt vmcnt(10)
	v_add_u32_e32 v18, v18, v6
	s_waitcnt vmcnt(9)
	v_add_u32_e32 v18, v18, v7
	s_waitcnt vmcnt(8)
	v_add_u32_e32 v18, v18, v8
	s_waitcnt vmcnt(7)
	v_add_u32_e32 v18, v18, v9
	s_waitcnt vmcnt(6)
	v_add_u32_e32 v18, v18, v10
	s_waitcnt vmcnt(5)
	v_add_u32_e32 v18, v18, v11
	s_waitcnt vmcnt(4)
	v_add_u32_e32 v18, v18, v12
	s_waitcnt vmcnt(3)
	v_add_u32_e32 v18, v18, v13
	s_waitcnt vmcnt(2)
	v_add_u32_e32 v18, v18, v14
	s_waitcnt vmcnt(1)
	v_add_u32_e32 v18, v18, v15
	s_waitcnt vmcnt(0)
	v_add_u32_e32 v18, v18, v16
	v_cmp_eq_u32_e32 vcc, s3, v18
	s_cbranch_vccnz .LBB0_2024
	s_and_b32 s5, s4, 0xff
	s_cmp_eq_u32 s5, 0
	s_mov_b64 s[86:87], -1
	s_sleep 4
	s_cbranch_scc1 .LBB0_2029
	s_and_b64 vcc, exec, s[86:87]
	s_cbranch_vccz .LBB0_2024
